# MLA staging block: LDS write order K nope, K pe, V (was K, V, pe) - LDS op order ahead of the rendezvous
# speedup vs baseline: 1.0175x; 1.0175x over previous
; __device__ __forceinline__ void pv_both_kp(f32x16& o0, f32x16& o1, int vb, bf16x8 pa0, bf16x8 pa1, bf16x8 pa2, bf16x8 pa3) {
;     ...
;     o1 = __builtin_amdgcn_mfma_f32_32x32x16_bf16(pa0, PK(m0, n0), o1, 0, 0, 0);
;     o1 = __builtin_amdgcn_mfma_f32_32x32x16_bf16(pa1, PK(m1, n1), o1, 0, 0, 0);
;     o1 = __builtin_amdgcn_mfma_f32_32x32x16_bf16(pa2, PK(m2, n2), o1, 0, 0, 0);
;     o1 = __builtin_amdgcn_mfma_f32_32x32x16_bf16(pa3, PK(m3, n3), o1, 0, 0, 0);
.Lmla_nobar4:
	v_mfma_f32_32x32x16_bf16 v[16:31], v[60:63], v[206:209], v[16:31]
	v_mfma_f32_32x32x16_bf16 v[16:31], v[56:59], v[150:153], v[16:31]
	s_cmp_lg_u64 s[44:45], 0
	s_cbranch_scc0 .Lmla_w1_tail
	s_waitcnt vmcnt(3)
	ds_write_b128 v196, v[120:123]
	s_cmp_lg_u32 s8, 0
	s_cbranch_scc0 .Lmla_nope_e
	ds_write_b128 v238, v[124:127] offset:128
.Lmla_nope_e:
	ds_write_b128 v197, v[128:131] offset:26624

; __device__ __forceinline__ void pv_both_kp(f32x16& o0, f32x16& o1, int vb, bf16x8 pa0, bf16x8 pa1, bf16x8 pa2, bf16x8 pa3) {
;     ...
;     o1 = __builtin_amdgcn_mfma_f32_32x32x16_bf16(pa0, PK(m0, n0), o1, 0, 0, 0);
;     o1 = __builtin_amdgcn_mfma_f32_32x32x16_bf16(pa1, PK(m1, n1), o1, 0, 0, 0);
;     o1 = __builtin_amdgcn_mfma_f32_32x32x16_bf16(pa2, PK(m2, n2), o1, 0, 0, 0);
;     o1 = __builtin_amdgcn_mfma_f32_32x32x16_bf16(pa3, PK(m3, n3), o1, 0, 0, 0);
.Lmla_nobar6:
	v_mfma_f32_32x32x16_bf16 v[16:31], v[92:95], v[190:193], v[16:31]
	v_mfma_f32_32x32x16_bf16 v[16:31], v[88:91], v[150:153], v[16:31]
	s_cmp_lt_i32 s47, s54
	s_cbranch_scc0 .Lmla_w2_tail
	s_waitcnt vmcnt(3)
	ds_write_b128 v200, v[136:139]
	s_cmp_lg_u32 s8, 0
	s_cbranch_scc0 .Lmla_nope_o
	ds_write_b128 v239, v[140:143] offset:128
.Lmla_nope_o:
	ds_write_b128 v201, v[132:135] offset:26624
